# norm+modulate phases: next row prefetched into spare registers while the current row is reduced and written (software pipelining); final norm gain loads hoisted
# baseline (speedup 1.0000x reference)
; __device__ __forceinline__ int opaque_tid() { int t = threadIdx.x; asm volatile("" : "+v"(t)); return t; }
; __device__ __forceinline__ int opaque_bid() { int t = blockIdx.x; asm volatile("" : "+s"(t)); return t; }
; __device__ __forceinline__ int opaque_gdim() { int t = gridDim.x; asm volatile("" : "+s"(t)); return t; }
; __device__ void norm_mod_phase(const float* srcL, const float* srcC, float* cpyL, float* cpyC, const float* g, const float* mod, bf16_t* TN, int nrows, const float* pb, int nsl) {
;     const int tid_ = opaque_tid(); const int lane = tid_ & 63, gw = opaque_bid() * 8 + (tid_ >> 6), nw = opaque_gdim() * 8;
;     for (int row = gw; row < nrows; row += nw) {
;         const bool lat = row < RL;
;         const float* sp = lat ? srcL + (size_t)row * 1024 : srcC + (size_t)(row - RL) * 1024;
;         const float* mp = mod + (lat ? (row >> 13) : 4) * 9216;
;         f32x4 v[4]; float ss = 0.f;
; #pragma unroll
;         for (int j = 0; j < 4; ++j) v[j] = *(const f32x4*)(sp + 256 * j + 4 * lane);
;         if (!lat && nsl > 0) {
;             for (int sl = 0; sl < nsl; ++sl) { const float* pp = pb + ((size_t)sl * 1024 + (row - RL)) * 1024;
; #pragma unroll
;                 for (int j = 0; j < 4; ++j) v[j] += *(const f32x4*)(pp + 256 * j + 4 * lane); }
;             float* wp = (float*)sp;
; #pragma unroll
;             for (int j = 0; j < 4; ++j) *(f32x4*)(wp + 256 * j + 4 * lane) = v[j];
;         }
; #pragma unroll
;         for (int j = 0; j < 4; ++j) ss += v[j][0] * v[j][0] + v[j][1] * v[j][1] + v[j][2] * v[j][2] + v[j][3] * v[j][3];
;         if (cpyL) { float* cp = lat ? cpyL + (size_t)row * 1024 : cpyC + (size_t)(row - RL) * 1024;
; #pragma unroll
;             for (int j = 0; j < 4; ++j) *(f32x4*)(cp + 256 * j + 4 * lane) = v[j]; }
;         ss = wave_sum(ss);
;         const float rstd = rsqrtf(ss * (1.0f / 1024.0f) + NEPS);
.LBB0_25:
	s_cmp_gt_i32 s63, 10
	s_mov_b64 s[0:1], -1
	s_cbranch_scc0 .LBB0_32
	v_readlane_b32 s0, v254, 58
	v_readlane_b32 s1, v254, 59
	s_mov_b32 s1, s0
	v_mov_b32_e32 v1, v189
	s_cmp_eq_u32 s1, 0
	s_mov_b32 s0, 0x8400
	s_mov_b32 s2, s66
	s_waitcnt vmcnt(0)
	v_ashrrev_i32_e32 v2, 6, v1
	s_cselect_b32 s0, s0, 0x8000
	s_nop 0
	v_lshl_add_u32 v18, s2, 3, v2
	s_mov_b32 s2, s94
	v_cmp_gt_i32_e32 vcc, s0, v18
	s_and_saveexec_b64 s[4:5], vcc
	s_cbranch_execz .LBB0_31
	v_readlane_b32 s12, v254, 56
	v_readlane_b32 s6, v254, 53
	v_readlane_b32 s13, v254, 57
	s_add_u32 s16, s12, 0x3240000
	v_readlane_b32 s7, v254, 54
	s_addc_u32 s17, s13, 0
	s_load_dwordx2 s[14:15], s[6:7], 0xb0
	s_load_dwordx2 s[10:11], s[6:7], 0x30
	s_mul_i32 s6, s1, 0x2d000
	s_mul_hi_i32 s3, s1, 0x2d000
	s_add_u32 s6, s12, s6
	s_addc_u32 s3, s13, s3
	s_add_u32 s6, s6, 0x3646000
	s_mulk_i32 s1, 0xc00
	s_addc_u32 s7, s3, 0
	s_lshl_b32 s8, s2, 3
	s_add_i32 s2, s1, 0x800
	s_ashr_i32 s3, s2, 31
	v_lshlrev_b32_e32 v2, 2, v1
	s_lshl_b64 s[2:3], s[2:3], 2
	v_and_b32_e32 v2, 0xfc, v2
	v_ashrrev_i32_e32 v19, 31, v18
	s_waitcnt lgkmcnt(0)
	s_add_u32 s2, s10, s2
	v_lshlrev_b32_e32 v4, 2, v2
	v_mov_b32_e32 v5, v0
	v_lshlrev_b64 v[10:11], 11, v[18:19]
	v_and_b32_e32 v1, 63, v1
	s_addc_u32 s3, s11, s3
	v_lshl_add_u64 v[6:7], s[12:13], 0, v[4:5]
	s_mov_b64 s[10:11], 0x1d362000
	v_lshl_or_b32 v10, v1, 3, v10
	v_lshl_add_u64 v[20:21], v[6:7], 0, s[10:11]
	v_lshl_add_u64 v[22:23], s[2:3], 0, v[4:5]
	v_or_b32_e32 v4, 0x100, v2
	v_or_b32_e32 v6, 0x200, v2
	v_or_b32_e32 v8, 0x300, v2
	v_lshl_add_u64 v[10:11], s[12:13], 0, v[10:11]
	s_mov_b64 s[2:3], 0x36de000
	s_ashr_i32 s9, s8, 31
	v_lshlrev_b32_e32 v26, 2, v2
	v_lshl_add_u64 v[24:25], v[10:11], 0, s[2:3]
	s_lshl_b64 s[10:11], s[8:9], 11
	s_mov_b64 s[12:13], 0
	v_mov_b32_e32 v1, s15
	v_mov_b32_e32 v42, s17
	v_mov_b32_e32 v43, s14
	v_mov_b32_e32 v44, s16
	v_mov_b32_e32 v28, v26
	v_mov_b32_e32 v29, v0
	v_lshlrev_b32_e32 v30, 2, v4
	v_lshlrev_b32_e32 v32, 2, v6
	v_lshlrev_b32_e32 v34, 2, v8
	v_add_u32_e32 v118, 0xffff8000, v18
	v_cmp_lt_i32_e32 vcc, s57, v18
	v_mov_b32_e32 v119, v0
	s_nop 1
	v_cndmask_b32_e32 v118, v18, v118, vcc
	v_cndmask_b32_e32 v123, v1, v42, vcc
	v_cndmask_b32_e32 v122, v43, v44, vcc
	v_lshlrev_b64 v[118:119], 12, v[118:119]
	v_lshl_add_u64 v[118:119], v[122:123], 0, v[118:119]
	v_lshl_add_u64 v[118:119], v[118:119], 0, v[28:29]
	global_load_dwordx4 v[102:105], v[118:119], off
	global_load_dwordx4 v[106:109], v[118:119], off offset:1024
	global_load_dwordx4 v[110:113], v[118:119], off offset:2048
	global_load_dwordx4 v[114:117], v[118:119], off offset:3072
	s_waitcnt vmcnt(0)
	s_branch .LBB0_29
.LBB0_28:
	s_or_b64 exec, exec, s[2:3]
	v_min_i32_e32 v27, 0x8000, v18
	v_ashrrev_i32_e32 v27, 13, v27
	v_mul_i32_i24_e32 v36, 0x2400, v27
	v_ashrrev_i32_e32 v37, 31, v36
	v_mov_b32_e32 v38, v11
	v_mov_b32_e32 v39, v15
	v_lshl_add_u64 v[40:41], v[36:37], 2, s[6:7]
	v_mov_b32_e32 v36, v10
	v_mov_b32_e32 v37, v14
	v_pk_mul_f32 v[38:39], v[38:39], v[38:39]
	v_mov_b32_e32 v46, v3
	v_pk_fma_f32 v[36:37], v[36:37], v[36:37], v[38:39]
	v_mov_b32_e32 v38, v12
	v_mov_b32_e32 v39, v16
	v_pk_fma_f32 v[36:37], v[38:39], v[38:39], v[36:37]
	v_mov_b32_e32 v38, v13
	v_mov_b32_e32 v39, v17
	v_mov_b32_e32 v47, v7
	v_pk_fma_f32 v[36:37], v[38:39], v[38:39], v[36:37]
	v_mov_b32_e32 v38, v2
	v_mov_b32_e32 v39, v6
	v_pk_mul_f32 v[46:47], v[46:47], v[46:47]
	v_mov_b32_e32 v31, v220
	v_pk_fma_f32 v[38:39], v[38:39], v[38:39], v[46:47]
	v_mov_b32_e32 v46, v4
	v_mov_b32_e32 v47, v8
	v_pk_fma_f32 v[38:39], v[46:47], v[46:47], v[38:39]
	v_mov_b32_e32 v46, v5
	v_mov_b32_e32 v47, v9
	v_pk_fma_f32 v[38:39], v[46:47], v[46:47], v[38:39]
	v_add_f32_e32 v27, v36, v37
	v_add_f32_e32 v27, v39, v27
	v_lshlrev_b32_e32 v31, 2, v31
	v_add_f32_e32 v27, v38, v27
	v_xor_b32_e32 v31, 0x80, v31
	ds_bpermute_b32 v31, v31, v27
	s_mov_b64 s[2:3], 0x1000
	v_lshl_add_u64 v[38:39], v[40:41], 0, s[2:3]
	v_mov_b32_e32 v96, v26
	v_mov_b32_e32 v97, v0
	v_lshl_add_u64 v[98:99], v[40:41], 0, v[96:97]
	v_lshl_add_u64 v[100:101], v[38:39], 0, v[96:97]
	global_load_dwordx4 v[46:49], v[22:23], off
	global_load_dwordx4 v[60:63], v[22:23], off offset:1024
	global_load_dwordx4 v[64:67], v[22:23], off offset:2048
	global_load_dwordx4 v[68:71], v[22:23], off offset:3072
	global_load_dwordx4 v[50:53], v[98:99], off
	global_load_dwordx4 v[72:75], v[98:99], off offset:1024
	global_load_dwordx4 v[76:79], v[98:99], off offset:2048
	global_load_dwordx4 v[80:83], v[98:99], off offset:3072
	global_load_dwordx4 v[54:57], v[100:101], off
	global_load_dwordx4 v[84:87], v[100:101], off offset:1024
	global_load_dwordx4 v[88:91], v[100:101], off offset:2048
	global_load_dwordx4 v[92:95], v[100:101], off offset:3072
	v_mov_b32_e32 v127, s0
	v_add_u32_e32 v126, s8, v18
	v_add_u32_e32 v127, -1, v127
	v_min_i32_e32 v126, v127, v126
	v_add_u32_e32 v118, 0xffff8000, v126
	v_cmp_lt_i32_e32 vcc, s57, v126
	v_mov_b32_e32 v119, v0
	s_nop 1
	v_cndmask_b32_e32 v118, v126, v118, vcc
	v_cndmask_b32_e32 v123, v1, v42, vcc
	v_cndmask_b32_e32 v122, v43, v44, vcc
	v_lshlrev_b64 v[118:119], 12, v[118:119]
	v_lshl_add_u64 v[118:119], v[122:123], 0, v[118:119]
	v_lshl_add_u64 v[118:119], v[118:119], 0, v[28:29]
	global_load_dwordx4 v[102:105], v[118:119], off
	global_load_dwordx4 v[106:109], v[118:119], off offset:1024
	global_load_dwordx4 v[110:113], v[118:119], off offset:2048
	global_load_dwordx4 v[114:117], v[118:119], off offset:3072
	v_mov_b32_e32 v33, v0
	v_mov_b32_e32 v35, v0
	s_waitcnt lgkmcnt(0)
	v_add_f32_e32 v27, v27, v31
	v_mov_b32_e32 v31, v220
	v_lshl_add_u64 v[18:19], v[18:19], 0, s[8:9]
	v_lshlrev_b32_e32 v31, 2, v31
	v_xor_b32_e32 v31, 64, v31
	ds_bpermute_b32 v31, v31, v27
	s_waitcnt lgkmcnt(0)
; __device__ __forceinline__ unsigned cvt_pk_bf16(float lo, float hi) { const f32x2_ v = {lo, hi}; return __builtin_bit_cast(unsigned, __builtin_convertvector(v, bf16x2_)); }
; __device__ void norm_mod_phase(const float* srcL, const float* srcC, float* cpyL, float* cpyC, const float* g, const float* mod, bf16_t* TN, int nrows, const float* pb, int nsl) {
;     ...
;         ss = wave_sum(ss);
;         const float rstd = rsqrtf(ss * (1.0f / 1024.0f) + NEPS);
; #pragma unroll
;         for (int j = 0; j < 4; ++j) {
;             const int col = 256 * j + 4 * lane;
;             const f32x4 gg = *(const f32x4*)(g + col), sh = *(const f32x4*)(mp + col), sc = *(const f32x4*)(mp + 1024 + col);
;             float o[4];
; #pragma unroll
;             for (int e = 0; e < 4; ++e) o[e] = (v[j][e] * rstd * gg[e]) * (1.0f + sc[e]) + sh[e];
;             u32x2 w; w.x = cvt_pk_bf16(o[0], o[1]); w.y = cvt_pk_bf16(o[2], o[3]);
;             *(u32x2*)(TN + (size_t)row * 1024 + col) = w;
;         }
	v_add_f32_e32 v27, v27, v31
	v_mov_b32_e32 v31, v220
	s_nop 0
	v_lshlrev_b32_e32 v31, 2, v31
	v_xor_b32_e32 v31, 32, v31
	ds_bpermute_b32 v31, v31, v27
	s_waitcnt lgkmcnt(0)
	v_add_f32_e32 v27, v27, v31
	v_mov_b32_e32 v31, v220
	s_nop 0
	v_lshlrev_b32_e32 v31, 2, v31
	v_xor_b32_e32 v31, 16, v31
	ds_bpermute_b32 v31, v31, v27
	s_waitcnt lgkmcnt(0)
	v_add_f32_e32 v27, v27, v31
	v_mov_b32_e32 v31, v220
	s_nop 0
	v_lshlrev_b32_e32 v31, 2, v31
	v_xor_b32_e32 v31, 8, v31
	ds_bpermute_b32 v31, v31, v27
	s_waitcnt lgkmcnt(0)
	v_add_f32_e32 v27, v27, v31
	v_mov_b32_e32 v31, v220
	v_lshlrev_b32_e32 v31, 2, v31
	v_xor_b32_e32 v31, 4, v31
	ds_bpermute_b32 v31, v31, v27
	s_waitcnt lgkmcnt(0)
	v_add_f32_e32 v27, v27, v31
	v_fmamk_f32 v27, v27, 0x3a800000, v188
	v_cmp_gt_f32_e32 vcc, s44, v27
	v_mul_f32_e32 v31, 0x4b800000, v27
	s_nop 0
	v_cndmask_b32_e32 v27, v27, v31, vcc
	v_rsq_f32_e32 v27, v27
	s_nop 0
	v_mul_f32_e32 v31, 0x45800000, v27
	v_cndmask_b32_e32 v36, v27, v31, vcc
	v_mov_b32_e32 v27, v0
	v_pk_mul_f32 v[14:15], v[14:15], v[36:37] op_sel_hi:[1,0]
	v_pk_mul_f32 v[16:17], v[16:17], v[36:37] op_sel_hi:[1,0]
	v_mov_b32_e32 v31, v0
	v_pk_mul_f32 v[10:11], v[10:11], v[36:37] op_sel_hi:[1,0]
	v_pk_mul_f32 v[12:13], v[12:13], v[36:37] op_sel_hi:[1,0]
	v_pk_mul_f32 v[6:7], v[6:7], v[36:37] op_sel_hi:[1,0]
	v_pk_mul_f32 v[8:9], v[8:9], v[36:37] op_sel_hi:[1,0]
	v_pk_mul_f32 v[2:3], v[2:3], v[36:37] op_sel_hi:[1,0]
	v_pk_mul_f32 v[4:5], v[4:5], v[36:37] op_sel_hi:[1,0]
	v_cmp_le_i32_e32 vcc, s0, v18
	s_or_b64 s[12:13], vcc, s[12:13]
	s_waitcnt vmcnt(4)
	v_pk_mul_f32 v[14:15], v[46:47], v[14:15]
	v_pk_mul_f32 v[16:17], v[48:49], v[16:17]
	v_pk_add_f32 v[46:47], v[54:55], 1.0 op_sel_hi:[1,0]
	s_nop 0
	v_pk_fma_f32 v[14:15], v[46:47], v[14:15], v[50:51]
	v_pk_add_f32 v[46:47], v[56:57], 1.0 op_sel_hi:[1,0]
	v_cvt_pk_bf16_f32 v14, v14, v15
	v_pk_fma_f32 v[16:17], v[46:47], v[16:17], v[52:53]
	s_nop 0
	v_cvt_pk_bf16_f32 v15, v16, v17
	global_store_dwordx2 v[24:25], v[14:15], off
	v_pk_mul_f32 v[10:11], v[60:61], v[10:11]
	v_pk_mul_f32 v[12:13], v[62:63], v[12:13]
	v_pk_add_f32 v[14:15], v[84:85], 1.0 op_sel_hi:[1,0]
	s_nop 0
	v_pk_fma_f32 v[10:11], v[14:15], v[10:11], v[72:73]
	v_pk_add_f32 v[14:15], v[86:87], 1.0 op_sel_hi:[1,0]
	v_cvt_pk_bf16_f32 v10, v10, v11
	v_pk_fma_f32 v[12:13], v[14:15], v[12:13], v[74:75]
	s_nop 0
	v_cvt_pk_bf16_f32 v11, v12, v13
	global_store_dwordx2 v[24:25], v[10:11], off offset:512
	v_pk_mul_f32 v[6:7], v[64:65], v[6:7]
	v_pk_mul_f32 v[8:9], v[66:67], v[8:9]
	v_pk_add_f32 v[10:11], v[88:89], 1.0 op_sel_hi:[1,0]
	s_nop 0
	v_pk_fma_f32 v[6:7], v[6:7], v[10:11], v[76:77]
	v_pk_add_f32 v[10:11], v[90:91], 1.0 op_sel_hi:[1,0]
	v_cvt_pk_bf16_f32 v6, v6, v7
	v_pk_fma_f32 v[8:9], v[8:9], v[10:11], v[78:79]
	s_nop 0
	v_cvt_pk_bf16_f32 v7, v8, v9
	global_store_dwordx2 v[24:25], v[6:7], off offset:1024
	v_pk_mul_f32 v[2:3], v[2:3], v[68:69]
	v_pk_mul_f32 v[4:5], v[4:5], v[70:71]
	v_pk_add_f32 v[6:7], v[92:93], 1.0 op_sel_hi:[1,0]
	s_nop 0
	v_pk_fma_f32 v[2:3], v[2:3], v[6:7], v[80:81]
	v_pk_add_f32 v[6:7], v[94:95], 1.0 op_sel_hi:[1,0]
	v_cvt_pk_bf16_f32 v2, v2, v3
	v_pk_fma_f32 v[4:5], v[4:5], v[6:7], v[82:83]
	s_nop 0
	v_cvt_pk_bf16_f32 v3, v4, v5
	global_store_dwordx2 v[24:25], v[2:3], off offset:1536
	v_lshl_add_u64 v[24:25], v[24:25], 0, s[10:11]
	s_andn2_b64 exec, exec, s[12:13]
	s_cbranch_execz .LBB0_31
; __device__ void norm_mod_phase(const float* srcL, const float* srcC, float* cpyL, float* cpyC, const float* g, const float* mod, bf16_t* TN, int nrows, const float* pb, int nsl) {
;     ...
;         const float* sp = lat ? srcL + (size_t)row * 1024 : srcC + (size_t)(row - RL) * 1024;
;         const float* mp = mod + (lat ? (row >> 13) : 4) * 9216;
;         f32x4 v[4]; float ss = 0.f;
; #pragma unroll
;         for (int j = 0; j < 4; ++j) v[j] = *(const f32x4*)(sp + 256 * j + 4 * lane);
;         if (!lat && nsl > 0) {
;             for (int sl = 0; sl < nsl; ++sl) { const float* pp = pb + ((size_t)sl * 1024 + (row - RL)) * 1024;
; #pragma unroll
;                 for (int j = 0; j < 4; ++j) v[j] += *(const f32x4*)(pp + 256 * j + 4 * lane); }
;             float* wp = (float*)sp;
; #pragma unroll
;             for (int j = 0; j < 4; ++j) *(f32x4*)(wp + 256 * j + 4 * lane) = v[j];
;         }
.LBB0_29:
	v_add_u32_e32 v38, 0xffff8000, v18
	v_cmp_lt_i32_e32 vcc, s57, v18
	v_mov_b32_e32 v39, v0
	s_nop 0
	v_cndmask_b32_e64 v3, v19, 0, vcc
	v_cndmask_b32_e32 v2, v18, v38, vcc
	v_cndmask_b32_e32 v5, v1, v42, vcc
	v_cndmask_b32_e32 v4, v43, v44, vcc
	v_lshlrev_b64 v[2:3], 12, v[2:3]
	v_lshl_add_u64 v[2:3], v[4:5], 0, v[2:3]
	v_lshl_add_u64 v[36:37], v[2:3], 0, v[28:29]
	s_waitcnt vmcnt(4)
	v_mov_b64_e32 v[14:15], v[102:103]
	v_mov_b64_e32 v[16:17], v[104:105]
	v_mov_b64_e32 v[10:11], v[106:107]
	v_mov_b64_e32 v[12:13], v[108:109]
	v_mov_b64_e32 v[6:7], v[110:111]
	v_mov_b64_e32 v[8:9], v[112:113]
	v_mov_b64_e32 v[2:3], v[114:115]
	v_mov_b64_e32 v[4:5], v[116:117]
	s_and_saveexec_b64 s[2:3], vcc
	s_cbranch_execz .LBB0_28
	v_lshlrev_b64 v[38:39], 12, v[38:39]
	v_lshl_add_u64 v[46:47], v[20:21], 0, v[38:39]
	global_load_dwordx4 v[60:63], v[46:47], off
	global_load_dwordx4 v[64:67], v[46:47], off offset:1024
	global_load_dwordx4 v[68:71], v[46:47], off offset:2048
	global_load_dwordx4 v[72:75], v[46:47], off offset:3072
	s_mov_b32 s1, 0x400000
	v_add_co_u32_e32 v48, vcc, s1, v46
	s_nop 1
	v_addc_co_u32_e32 v49, vcc, 0, v47, vcc
	global_load_dwordx4 v[76:79], v[48:49], off
	global_load_dwordx4 v[80:83], v[48:49], off offset:1024
	global_load_dwordx4 v[84:87], v[48:49], off offset:2048
	global_load_dwordx4 v[88:91], v[48:49], off offset:3072
	s_mov_b32 s1, 0x800000
	v_add_co_u32_e32 v48, vcc, s1, v46
	s_nop 1
	v_addc_co_u32_e32 v49, vcc, 0, v47, vcc
	global_load_dwordx4 v[92:95], v[48:49], off
	global_load_dwordx4 v[96:99], v[48:49], off offset:1024
	global_load_dwordx4 v[100:103], v[48:49], off offset:2048
	global_load_dwordx4 v[104:107], v[48:49], off offset:3072
	s_mov_b32 s1, 0xc00000
	v_add_co_u32_e32 v48, vcc, s1, v46
	s_nop 1
	v_addc_co_u32_e32 v49, vcc, 0, v47, vcc
	global_load_dwordx4 v[108:111], v[48:49], off
	global_load_dwordx4 v[112:115], v[48:49], off offset:1024
	global_load_dwordx4 v[116:119], v[48:49], off offset:2048
	global_load_dwordx4 v[120:123], v[48:49], off offset:3072
	s_waitcnt vmcnt(15)
	v_pk_add_f32 v[14:15], v[14:15], v[60:61]
	v_pk_add_f32 v[16:17], v[16:17], v[62:63]
	s_waitcnt vmcnt(14)
	v_pk_add_f32 v[10:11], v[10:11], v[64:65]
	v_pk_add_f32 v[12:13], v[12:13], v[66:67]
	s_waitcnt vmcnt(13)
	v_pk_add_f32 v[6:7], v[6:7], v[68:69]
	v_pk_add_f32 v[8:9], v[8:9], v[70:71]
	s_waitcnt vmcnt(12)
	v_pk_add_f32 v[2:3], v[2:3], v[72:73]
	v_pk_add_f32 v[4:5], v[4:5], v[74:75]
	s_waitcnt vmcnt(11)
	v_pk_add_f32 v[14:15], v[14:15], v[76:77]
	v_pk_add_f32 v[16:17], v[16:17], v[78:79]
	s_waitcnt vmcnt(10)
	v_pk_add_f32 v[10:11], v[10:11], v[80:81]
	v_pk_add_f32 v[12:13], v[12:13], v[82:83]
	s_waitcnt vmcnt(9)
	v_pk_add_f32 v[6:7], v[6:7], v[84:85]
	v_pk_add_f32 v[8:9], v[8:9], v[86:87]
	s_waitcnt vmcnt(8)
	v_pk_add_f32 v[2:3], v[2:3], v[88:89]
	v_pk_add_f32 v[4:5], v[4:5], v[90:91]
	s_waitcnt vmcnt(7)
	v_pk_add_f32 v[14:15], v[14:15], v[92:93]
	v_pk_add_f32 v[16:17], v[16:17], v[94:95]
	s_waitcnt vmcnt(6)
	v_pk_add_f32 v[10:11], v[10:11], v[96:97]
	v_pk_add_f32 v[12:13], v[12:13], v[98:99]
	s_waitcnt vmcnt(5)
	v_pk_add_f32 v[6:7], v[6:7], v[100:101]
	v_pk_add_f32 v[8:9], v[8:9], v[102:103]
	s_waitcnt vmcnt(4)
	v_pk_add_f32 v[2:3], v[2:3], v[104:105]
	v_pk_add_f32 v[4:5], v[4:5], v[106:107]
	s_waitcnt vmcnt(3)
	v_pk_add_f32 v[14:15], v[14:15], v[108:109]
	v_pk_add_f32 v[16:17], v[16:17], v[110:111]
	s_waitcnt vmcnt(2)
	v_pk_add_f32 v[10:11], v[10:11], v[112:113]
	v_pk_add_f32 v[12:13], v[12:13], v[114:115]
	s_waitcnt vmcnt(1)
	v_pk_add_f32 v[6:7], v[6:7], v[116:117]
	v_pk_add_f32 v[8:9], v[8:9], v[118:119]
	s_waitcnt vmcnt(0)
	v_pk_add_f32 v[2:3], v[2:3], v[120:121]
	v_pk_add_f32 v[4:5], v[4:5], v[122:123]
	global_store_dwordx4 v[36:37], v[14:17], off
	global_store_dwordx4 v[36:37], v[10:13], off offset:1024
	global_store_dwordx4 v[36:37], v[6:9], off offset:2048
	global_store_dwordx4 v[36:37], v[2:5], off offset:3072
	s_branch .LBB0_28

; __device__ __forceinline__ int opaque_tid() { int t = threadIdx.x; asm volatile("" : "+v"(t)); return t; }
; __device__ __forceinline__ int opaque_bid() { int t = blockIdx.x; asm volatile("" : "+s"(t)); return t; }
; __device__ __forceinline__ int opaque_gdim() { int t = gridDim.x; asm volatile("" : "+s"(t)); return t; }
; __device__ void norm_mod_phase(const float* srcL, const float* srcC, float* cpyL, float* cpyC, const float* g, const float* mod, bf16_t* TN, int nrows, const float* pb, int nsl) {
;     const int tid_ = opaque_tid(); const int lane = tid_ & 63, gw = opaque_bid() * 8 + (tid_ >> 6), nw = opaque_gdim() * 8;
;     for (int row = gw; row < nrows; row += nw) {
;         const bool lat = row < RL;
;         const float* sp = lat ? srcL + (size_t)row * 1024 : srcC + (size_t)(row - RL) * 1024;
;         const float* mp = mod + (lat ? (row >> 13) : 4) * 9216;
;         f32x4 v[4]; float ss = 0.f;
; #pragma unroll
;         for (int j = 0; j < 4; ++j) v[j] = *(const f32x4*)(sp + 256 * j + 4 * lane);
;         if (!lat && nsl > 0) {
;             for (int sl = 0; sl < nsl; ++sl) { const float* pp = pb + ((size_t)sl * 1024 + (row - RL)) * 1024;
; #pragma unroll
;                 for (int j = 0; j < 4; ++j) v[j] += *(const f32x4*)(pp + 256 * j + 4 * lane); }
;             float* wp = (float*)sp;
; #pragma unroll
;             for (int j = 0; j < 4; ++j) *(f32x4*)(wp + 256 * j + 4 * lane) = v[j];
;         }
; #pragma unroll
;         for (int j = 0; j < 4; ++j) ss += v[j][0] * v[j][0] + v[j][1] * v[j][1] + v[j][2] * v[j][2] + v[j][3] * v[j][3];
;         if (cpyL) { float* cp = lat ? cpyL + (size_t)row * 1024 : cpyC + (size_t)(row - RL) * 1024;
; #pragma unroll
;             for (int j = 0; j < 4; ++j) *(f32x4*)(cp + 256 * j + 4 * lane) = v[j]; }
;         ss = wave_sum(ss);
;         const float rstd = rsqrtf(ss * (1.0f / 1024.0f) + NEPS);
.LBB0_528:
	s_andn2_b64 vcc, exec, s[0:1]
	s_cbranch_vccnz .LBB0_537
	s_cmp_gt_i32 s63, 3
	s_mov_b64 s[0:1], -1
	s_cbranch_scc0 .LBB0_536
	v_readlane_b32 s0, v254, 58
	s_mov_b32 s2, s0
	v_mov_b32_e32 v1, v189
	s_mov_b32 s0, s66
	s_mov_b32 s3, s94
	s_waitcnt vmcnt(0)
	v_ashrrev_i32_e32 v2, 6, v1
	v_lshl_add_u32 v18, s0, 3, v2
	s_mov_b32 s0, 0x8400
	v_cmp_gt_i32_e32 vcc, s0, v18
	v_readlane_b32 s1, v254, 59
	s_and_saveexec_b64 s[4:5], vcc
	s_cbranch_execz .LBB0_535
	v_readlane_b32 s14, v254, 56
	v_readlane_b32 s8, v254, 53
	v_readlane_b32 s15, v254, 57
	s_add_u32 s0, s14, 0x3240000
	v_readlane_b32 s9, v254, 54
	s_addc_u32 s1, s15, 0
	s_load_dwordx2 s[6:7], s[8:9], 0xb0
	s_load_dwordx2 s[12:13], s[8:9], 0x30
	s_mul_i32 s9, s2, 0x2d000
	s_mul_hi_i32 s8, s2, 0x2d000
	s_add_u32 s9, s14, s9
	s_addc_u32 s10, s15, s8
	s_add_u32 s8, s9, 0x3643000
	s_mulk_i32 s2, 0xc00
	s_addc_u32 s9, s10, 0
	s_addk_i32 s2, 0x400
	s_lshl_b32 s10, s3, 3
	s_ashr_i32 s3, s2, 31
	v_lshlrev_b32_e32 v2, 2, v1
	s_lshl_b64 s[2:3], s[2:3], 2
	v_and_b32_e32 v2, 0xfc, v2
	v_ashrrev_i32_e32 v19, 31, v18
	s_waitcnt lgkmcnt(0)
	s_add_u32 s2, s12, s2
	v_lshlrev_b32_e32 v4, 2, v2
	v_mov_b32_e32 v5, v0
	v_lshlrev_b64 v[10:11], 11, v[18:19]
	v_and_b32_e32 v1, 63, v1
	s_addc_u32 s3, s13, s3
	v_lshl_add_u64 v[6:7], s[14:15], 0, v[4:5]
	s_mov_b64 s[12:13], 0x1d362000
	v_lshl_or_b32 v10, v1, 3, v10
	v_lshl_add_u64 v[20:21], v[6:7], 0, s[12:13]
	v_lshl_add_u64 v[22:23], s[2:3], 0, v[4:5]
	v_or_b32_e32 v4, 0x100, v2
	v_or_b32_e32 v6, 0x200, v2
	v_or_b32_e32 v8, 0x300, v2
	v_lshl_add_u64 v[10:11], s[14:15], 0, v[10:11]
	s_mov_b64 s[2:3], 0x36de000
	s_ashr_i32 s11, s10, 31
	v_lshl_add_u64 v[24:25], v[10:11], 0, s[2:3]
	s_lshl_b64 s[12:13], s[10:11], 11
	s_mov_b64 s[14:15], 0
	v_lshlrev_b32_e32 v26, 2, v2
	v_lshlrev_b32_e32 v28, 2, v4
	v_lshlrev_b32_e32 v30, 2, v6
	v_lshlrev_b32_e32 v32, 2, v8
	v_add_u32_e32 v118, 0xffff8000, v18
	v_cmp_lt_i32_e32 vcc, s57, v18
	v_mov_b32_e32 v120, s7
	v_mov_b32_e32 v121, s1
	v_mov_b32_e32 v119, v0
	v_cndmask_b32_e32 v118, v18, v118, vcc
	v_cndmask_b32_e32 v123, v120, v121, vcc
	v_mov_b32_e32 v120, s6
	v_mov_b32_e32 v121, s0
	v_cndmask_b32_e32 v122, v120, v121, vcc
	v_lshlrev_b64 v[118:119], 12, v[118:119]
	v_lshl_add_u64 v[118:119], v[122:123], 0, v[118:119]
	v_mov_b32_e32 v124, v26
	v_mov_b32_e32 v125, v0
	v_lshl_add_u64 v[118:119], v[118:119], 0, v[124:125]
	global_load_dwordx4 v[102:105], v[118:119], off
	global_load_dwordx4 v[106:109], v[118:119], off offset:1024
	global_load_dwordx4 v[110:113], v[118:119], off offset:2048
	global_load_dwordx4 v[114:117], v[118:119], off offset:3072
	s_waitcnt vmcnt(0)
	s_branch .LBB0_533
.LBB0_532:
	s_or_b64 exec, exec, s[2:3]
	v_min_i32_e32 v1, 0x8000, v18
	v_ashrrev_i32_e32 v1, 13, v1
	v_mul_i32_i24_e32 v34, 0x2400, v1
	v_ashrrev_i32_e32 v35, 31, v34
	v_mov_b32_e32 v36, v7
	v_mov_b32_e32 v37, v11
	v_lshl_add_u64 v[38:39], v[34:35], 2, s[8:9]
	v_mov_b32_e32 v34, v6
	v_mov_b32_e32 v35, v10
	v_pk_mul_f32 v[36:37], v[36:37], v[36:37]
	v_mov_b32_e32 v40, v15
	v_pk_fma_f32 v[34:35], v[34:35], v[34:35], v[36:37]
	v_mov_b32_e32 v36, v8
	v_mov_b32_e32 v37, v12
	v_pk_fma_f32 v[34:35], v[36:37], v[36:37], v[34:35]
	v_mov_b32_e32 v36, v9
	v_mov_b32_e32 v37, v13
	v_mov_b32_e32 v41, v3
	v_pk_fma_f32 v[34:35], v[36:37], v[36:37], v[34:35]
	v_mov_b32_e32 v36, v14
	v_mov_b32_e32 v37, v2
	v_pk_mul_f32 v[40:41], v[40:41], v[40:41]
	v_mov_b32_e32 v29, v220
	v_pk_fma_f32 v[36:37], v[36:37], v[36:37], v[40:41]
	v_mov_b32_e32 v40, v16
	v_mov_b32_e32 v41, v4
	v_pk_fma_f32 v[36:37], v[40:41], v[40:41], v[36:37]
	v_mov_b32_e32 v40, v17
	v_mov_b32_e32 v41, v5
	v_pk_fma_f32 v[36:37], v[40:41], v[40:41], v[36:37]
	v_add_f32_e32 v1, v34, v35
	v_add_f32_e32 v1, v37, v1
	v_lshlrev_b32_e32 v29, 2, v29
	v_add_f32_e32 v1, v36, v1
	v_xor_b32_e32 v29, 0x80, v29
	ds_bpermute_b32 v29, v29, v1
	s_mov_b64 s[2:3], 0x1000
	v_lshl_add_u64 v[36:37], v[38:39], 0, s[2:3]
	v_lshl_add_u64 v[38:39], v[38:39], 0, v[26:27]
	v_lshl_add_u64 v[48:49], v[36:37], 0, v[26:27]
	s_waitcnt lgkmcnt(0)
	v_add_f32_e32 v1, v1, v29
	v_mov_b32_e32 v29, v220
	v_mov_b32_e32 v31, v0
	v_lshlrev_b32_e32 v29, 2, v29
	v_xor_b32_e32 v29, 64, v29
	ds_bpermute_b32 v29, v29, v1
	v_mov_b32_e32 v33, v0
	v_lshl_add_u64 v[18:19], v[18:19], 0, s[10:11]
	s_waitcnt lgkmcnt(0)
	v_add_f32_e32 v1, v1, v29
	v_mov_b32_e32 v29, v220
	s_nop 0
	v_lshlrev_b32_e32 v29, 2, v29
	v_xor_b32_e32 v29, 32, v29
	ds_bpermute_b32 v29, v29, v1
	s_waitcnt lgkmcnt(0)
	v_add_f32_e32 v1, v1, v29
	v_mov_b32_e32 v29, v220
	s_nop 0
	v_lshlrev_b32_e32 v29, 2, v29
	v_xor_b32_e32 v29, 16, v29
	ds_bpermute_b32 v29, v29, v1
	s_waitcnt lgkmcnt(0)
	v_add_f32_e32 v1, v1, v29
	v_mov_b32_e32 v29, v220
	s_nop 0
	v_lshlrev_b32_e32 v29, 2, v29
	v_xor_b32_e32 v29, 8, v29
	ds_bpermute_b32 v29, v29, v1
	s_waitcnt lgkmcnt(0)
	v_add_f32_e32 v1, v1, v29
	v_mov_b32_e32 v29, v220
	global_load_dwordx4 v[40:43], v[22:23], off
	global_load_dwordx4 v[44:47], v[38:39], off
	global_load_dwordx4 v[60:63], v[22:23], off offset:1024
	global_load_dwordx4 v[64:67], v[22:23], off offset:2048
	global_load_dwordx4 v[68:71], v[22:23], off offset:3072
	global_load_dwordx4 v[72:75], v[38:39], off offset:1024
	global_load_dwordx4 v[76:79], v[38:39], off offset:2048
	global_load_dwordx4 v[80:83], v[38:39], off offset:3072
	global_load_dwordx4 v[84:87], v[48:49], off offset:1024
	global_load_dwordx4 v[88:91], v[48:49], off offset:2048
	global_load_dwordx4 v[92:95], v[48:49], off offset:3072
	v_lshlrev_b32_e32 v29, 2, v29
	global_load_dwordx4 v[48:51], v[48:49], off
	v_min_i32_e32 v126, s45, v18
	v_add_u32_e32 v118, 0xffff8000, v126
	v_cmp_lt_i32_e32 vcc, s57, v126
	v_mov_b32_e32 v120, s7
	v_mov_b32_e32 v121, s1
	v_mov_b32_e32 v119, v0
	v_cndmask_b32_e32 v118, v126, v118, vcc
	v_cndmask_b32_e32 v123, v120, v121, vcc
	v_mov_b32_e32 v120, s6
	v_mov_b32_e32 v121, s0
	v_cndmask_b32_e32 v122, v120, v121, vcc
	v_lshlrev_b64 v[118:119], 12, v[118:119]
	v_lshl_add_u64 v[118:119], v[122:123], 0, v[118:119]
	v_mov_b32_e32 v124, v26
	v_mov_b32_e32 v125, v0
	v_lshl_add_u64 v[118:119], v[118:119], 0, v[124:125]
	global_load_dwordx4 v[102:105], v[118:119], off
	global_load_dwordx4 v[106:109], v[118:119], off offset:1024
	global_load_dwordx4 v[110:113], v[118:119], off offset:2048
	global_load_dwordx4 v[114:117], v[118:119], off offset:3072
	v_xor_b32_e32 v29, 4, v29
	ds_bpermute_b32 v29, v29, v1
	s_waitcnt lgkmcnt(0)
; __device__ __forceinline__ unsigned cvt_pk_bf16(float lo, float hi) { const f32x2_ v = {lo, hi}; return __builtin_bit_cast(unsigned, __builtin_convertvector(v, bf16x2_)); }
; __device__ void norm_mod_phase(const float* srcL, const float* srcC, float* cpyL, float* cpyC, const float* g, const float* mod, bf16_t* TN, int nrows, const float* pb, int nsl) {
;     ...
;     for (int row = gw; row < nrows; row += nw) {
;         const bool lat = row < RL;
;         const float* sp = lat ? srcL + (size_t)row * 1024 : srcC + (size_t)(row - RL) * 1024;
;         const float* mp = mod + (lat ? (row >> 13) : 4) * 9216;
;         f32x4 v[4]; float ss = 0.f;
; #pragma unroll
;         for (int j = 0; j < 4; ++j) v[j] = *(const f32x4*)(sp + 256 * j + 4 * lane);
;     ...
;         ss = wave_sum(ss);
;         const float rstd = rsqrtf(ss * (1.0f / 1024.0f) + NEPS);
; #pragma unroll
;         for (int j = 0; j < 4; ++j) {
;             const int col = 256 * j + 4 * lane;
;             const f32x4 gg = *(const f32x4*)(g + col), sh = *(const f32x4*)(mp + col), sc = *(const f32x4*)(mp + 1024 + col);
;             float o[4];
; #pragma unroll
;             for (int e = 0; e < 4; ++e) o[e] = (v[j][e] * rstd * gg[e]) * (1.0f + sc[e]) + sh[e];
;             u32x2 w; w.x = cvt_pk_bf16(o[0], o[1]); w.y = cvt_pk_bf16(o[2], o[3]);
;             *(u32x2*)(TN + (size_t)row * 1024 + col) = w;
;         }
	v_add_f32_e32 v1, v1, v29
	v_fmamk_f32 v1, v1, 0x3a800000, v188
	v_cmp_gt_f32_e32 vcc, s44, v1
	v_mul_f32_e32 v29, 0x4b800000, v1
	s_nop 0
	v_cndmask_b32_e32 v1, v1, v29, vcc
	v_rsq_f32_e32 v1, v1
	s_nop 0
	v_mul_f32_e32 v29, 0x45800000, v1
	v_cndmask_b32_e32 v34, v1, v29, vcc
	v_pk_mul_f32 v[10:11], v[10:11], v[34:35] op_sel_hi:[1,0]
	v_pk_mul_f32 v[12:13], v[12:13], v[34:35] op_sel_hi:[1,0]
	v_mov_b32_e32 v29, v0
	v_pk_mul_f32 v[6:7], v[6:7], v[34:35] op_sel_hi:[1,0]
	v_pk_mul_f32 v[8:9], v[8:9], v[34:35] op_sel_hi:[1,0]
	v_pk_mul_f32 v[2:3], v[2:3], v[34:35] op_sel_hi:[1,0]
	v_pk_mul_f32 v[4:5], v[4:5], v[34:35] op_sel_hi:[1,0]
	v_pk_mul_f32 v[14:15], v[14:15], v[34:35] op_sel_hi:[1,0]
	v_cmp_lt_i32_e32 vcc, s45, v18
	s_or_b64 s[14:15], vcc, s[14:15]
	s_waitcnt vmcnt(4)
	v_pk_mul_f32 v[10:11], v[40:41], v[10:11]
	v_pk_mul_f32 v[12:13], v[42:43], v[12:13]
	v_pk_add_f32 v[40:41], v[48:49], 1.0 op_sel_hi:[1,0]
	s_nop 0
	v_pk_fma_f32 v[10:11], v[40:41], v[10:11], v[44:45]
	v_pk_add_f32 v[40:41], v[50:51], 1.0 op_sel_hi:[1,0]
	v_cvt_pk_bf16_f32 v10, v10, v11
	v_pk_fma_f32 v[12:13], v[40:41], v[12:13], v[46:47]
	s_nop 0
	v_cvt_pk_bf16_f32 v11, v12, v13
	global_store_dwordx2 v[24:25], v[10:11], off
	v_pk_mul_f32 v[6:7], v[60:61], v[6:7]
	v_pk_mul_f32 v[8:9], v[62:63], v[8:9]
	v_pk_add_f32 v[10:11], v[84:85], 1.0 op_sel_hi:[1,0]
	s_nop 0
	v_pk_fma_f32 v[6:7], v[10:11], v[6:7], v[72:73]
	v_pk_add_f32 v[10:11], v[86:87], 1.0 op_sel_hi:[1,0]
	v_cvt_pk_bf16_f32 v6, v6, v7
	v_pk_fma_f32 v[8:9], v[10:11], v[8:9], v[74:75]
	s_nop 0
	v_cvt_pk_bf16_f32 v7, v8, v9
	global_store_dwordx2 v[24:25], v[6:7], off offset:512
	v_pk_mul_f32 v[2:3], v[64:65], v[2:3]
	v_pk_mul_f32 v[4:5], v[66:67], v[4:5]
	v_pk_add_f32 v[6:7], v[88:89], 1.0 op_sel_hi:[1,0]
	s_nop 0
	v_pk_fma_f32 v[2:3], v[2:3], v[6:7], v[76:77]
	v_pk_add_f32 v[6:7], v[90:91], 1.0 op_sel_hi:[1,0]
	v_cvt_pk_bf16_f32 v2, v2, v3
	v_pk_fma_f32 v[4:5], v[4:5], v[6:7], v[78:79]
	s_nop 0
	v_cvt_pk_bf16_f32 v3, v4, v5
	global_store_dwordx2 v[24:25], v[2:3], off offset:1024
	v_pk_mul_f32 v[2:3], v[14:15], v[68:69]
	v_pk_add_f32 v[10:11], v[92:93], 1.0 op_sel_hi:[1,0]
	s_nop 0
	v_pk_fma_f32 v[2:3], v[2:3], v[10:11], v[80:81]
	v_pk_mul_f32 v[6:7], v[16:17], v[34:35] op_sel_hi:[1,0]
	v_cvt_pk_bf16_f32 v2, v2, v3
	v_pk_mul_f32 v[4:5], v[6:7], v[70:71]
	v_pk_add_f32 v[6:7], v[94:95], 1.0 op_sel_hi:[1,0]
	s_nop 0
	v_pk_fma_f32 v[4:5], v[4:5], v[6:7], v[82:83]
	s_nop 0
	v_cvt_pk_bf16_f32 v3, v4, v5
	global_store_dwordx2 v[24:25], v[2:3], off offset:1536
	v_lshl_add_u64 v[24:25], v[24:25], 0, s[12:13]
	s_andn2_b64 exec, exec, s[14:15]
	s_cbranch_execz .LBB0_535
.LBB0_533:
	v_add_u32_e32 v36, 0xffff8000, v18
	v_cmp_lt_i32_e32 vcc, s57, v18
	v_mov_b32_e32 v1, s7
	v_mov_b32_e32 v4, s1
	v_cndmask_b32_e64 v3, v19, 0, vcc
	v_cndmask_b32_e32 v2, v18, v36, vcc
	v_cndmask_b32_e32 v5, v1, v4, vcc
	v_mov_b32_e32 v1, s6
	v_mov_b32_e32 v4, s0
	v_cndmask_b32_e32 v4, v1, v4, vcc
	v_lshlrev_b64 v[2:3], 12, v[2:3]
	v_lshl_add_u64 v[2:3], v[4:5], 0, v[2:3]
	v_mov_b32_e32 v27, v0
	v_lshl_add_u64 v[34:35], v[2:3], 0, v[26:27]
	s_waitcnt vmcnt(4)
	v_mov_b64_e32 v[10:11], v[102:103]
	v_mov_b64_e32 v[12:13], v[104:105]
	v_mov_b64_e32 v[6:7], v[106:107]
	v_mov_b64_e32 v[8:9], v[108:109]
	v_mov_b64_e32 v[2:3], v[110:111]
	v_mov_b64_e32 v[4:5], v[112:113]
	v_mov_b64_e32 v[14:15], v[114:115]
	v_mov_b64_e32 v[16:17], v[116:117]
	v_mov_b32_e32 v37, v0
	s_and_saveexec_b64 s[2:3], vcc
	s_cbranch_execz .LBB0_532
	v_lshlrev_b64 v[36:37], 12, v[36:37]
	v_lshl_add_u64 v[36:37], v[20:21], 0, v[36:37]
	global_load_dwordx4 v[60:63], v[36:37], off
	global_load_dwordx4 v[64:67], v[36:37], off offset:1024
	global_load_dwordx4 v[68:71], v[36:37], off offset:2048
	global_load_dwordx4 v[72:75], v[36:37], off offset:3072
	s_mov_b32 s16, 0x400000
	v_add_co_u32_e32 v42, vcc, s16, v36
	s_nop 1
	v_addc_co_u32_e32 v43, vcc, 0, v37, vcc
	global_load_dwordx4 v[76:79], v[42:43], off
	global_load_dwordx4 v[80:83], v[42:43], off offset:1024
	global_load_dwordx4 v[84:87], v[42:43], off offset:2048
	global_load_dwordx4 v[88:91], v[42:43], off offset:3072
	s_mov_b32 s16, 0x800000
	v_add_co_u32_e32 v42, vcc, s16, v36
	s_nop 1
	v_addc_co_u32_e32 v43, vcc, 0, v37, vcc
	global_load_dwordx4 v[92:95], v[42:43], off
	global_load_dwordx4 v[96:99], v[42:43], off offset:1024
	global_load_dwordx4 v[100:103], v[42:43], off offset:2048
	global_load_dwordx4 v[104:107], v[42:43], off offset:3072
	s_mov_b32 s16, 0xc00000
	v_add_co_u32_e32 v42, vcc, s16, v36
	s_nop 1
	v_addc_co_u32_e32 v43, vcc, 0, v37, vcc
	global_load_dwordx4 v[108:111], v[42:43], off
	global_load_dwordx4 v[112:115], v[42:43], off offset:1024
	global_load_dwordx4 v[116:119], v[42:43], off offset:2048
	global_load_dwordx4 v[120:123], v[42:43], off offset:3072
	s_mov_b32 s16, 0x1000000
	v_add_co_u32_e32 v42, vcc, s16, v36
	s_nop 1
	v_addc_co_u32_e32 v43, vcc, 0, v37, vcc
	global_load_dwordx4 v[124:127], v[42:43], off
	global_load_dwordx4 v[128:131], v[42:43], off offset:1024
	global_load_dwordx4 v[132:135], v[42:43], off offset:2048
	global_load_dwordx4 v[136:139], v[42:43], off offset:3072
	s_mov_b32 s16, 0x1400000
	v_add_co_u32_e32 v42, vcc, s16, v36
	s_nop 1
	v_addc_co_u32_e32 v43, vcc, 0, v37, vcc
	global_load_dwordx4 v[140:143], v[42:43], off
	global_load_dwordx4 v[144:147], v[42:43], off offset:1024
	global_load_dwordx4 v[148:151], v[42:43], off offset:2048
	global_load_dwordx4 v[152:155], v[42:43], off offset:3072
	s_mov_b32 s16, 0x1800000
	v_add_co_u32_e32 v42, vcc, s16, v36
	s_nop 1
	v_addc_co_u32_e32 v43, vcc, 0, v37, vcc
	global_load_dwordx4 v[156:159], v[42:43], off
	global_load_dwordx4 v[160:163], v[42:43], off offset:1024
	global_load_dwordx4 v[164:167], v[42:43], off offset:2048
	global_load_dwordx4 v[168:171], v[42:43], off offset:3072
	s_mov_b32 s16, 0x1c00000
	v_add_co_u32_e32 v42, vcc, s16, v36
	s_nop 1
	v_addc_co_u32_e32 v43, vcc, 0, v37, vcc
	global_load_dwordx4 v[172:175], v[42:43], off
	global_load_dwordx4 v[176:179], v[42:43], off offset:1024
	global_load_dwordx4 v[180:183], v[42:43], off offset:2048
	global_load_dwordx4 v[184:187], v[42:43], off offset:3072
	s_waitcnt vmcnt(31)
; __device__ void norm_mod_phase(const float* srcL, const float* srcC, float* cpyL, float* cpyC, const float* g, const float* mod, bf16_t* TN, int nrows, const float* pb, int nsl) {
;     ...
;         if (!lat && nsl > 0) {
;             for (int sl = 0; sl < nsl; ++sl) { const float* pp = pb + ((size_t)sl * 1024 + (row - RL)) * 1024;
; #pragma unroll
;                 for (int j = 0; j < 4; ++j) v[j] += *(const f32x4*)(pp + 256 * j + 4 * lane); }
;             float* wp = (float*)sp;
; #pragma unroll
;             for (int j = 0; j < 4; ++j) *(f32x4*)(wp + 256 * j + 4 * lane) = v[j];
;         }
	v_pk_add_f32 v[10:11], v[10:11], v[60:61]
	v_pk_add_f32 v[12:13], v[12:13], v[62:63]
	s_waitcnt vmcnt(30)
	v_pk_add_f32 v[6:7], v[6:7], v[64:65]
	v_pk_add_f32 v[8:9], v[8:9], v[66:67]
	s_waitcnt vmcnt(29)
	v_pk_add_f32 v[2:3], v[2:3], v[68:69]
	v_pk_add_f32 v[4:5], v[4:5], v[70:71]
	s_waitcnt vmcnt(28)
	v_pk_add_f32 v[14:15], v[14:15], v[72:73]
	v_pk_add_f32 v[16:17], v[16:17], v[74:75]
	s_mov_b32 s16, 0x2000000
	v_add_co_u32_e32 v42, vcc, s16, v36
	s_nop 1
	v_addc_co_u32_e32 v43, vcc, 0, v37, vcc
	global_load_dwordx4 v[60:63], v[42:43], off
	global_load_dwordx4 v[64:67], v[42:43], off offset:1024
	global_load_dwordx4 v[68:71], v[42:43], off offset:2048
	global_load_dwordx4 v[72:75], v[42:43], off offset:3072
	s_waitcnt vmcnt(31)
	v_pk_add_f32 v[10:11], v[10:11], v[76:77]
	v_pk_add_f32 v[12:13], v[12:13], v[78:79]
	s_waitcnt vmcnt(30)
	v_pk_add_f32 v[6:7], v[6:7], v[80:81]
	v_pk_add_f32 v[8:9], v[8:9], v[82:83]
	s_waitcnt vmcnt(29)
	v_pk_add_f32 v[2:3], v[2:3], v[84:85]
	v_pk_add_f32 v[4:5], v[4:5], v[86:87]
	s_waitcnt vmcnt(28)
	v_pk_add_f32 v[14:15], v[14:15], v[88:89]
	v_pk_add_f32 v[16:17], v[16:17], v[90:91]
	s_mov_b32 s16, 0x2400000
	v_add_co_u32_e32 v42, vcc, s16, v36
	s_nop 1
	v_addc_co_u32_e32 v43, vcc, 0, v37, vcc
	global_load_dwordx4 v[76:79], v[42:43], off
	global_load_dwordx4 v[80:83], v[42:43], off offset:1024
	global_load_dwordx4 v[84:87], v[42:43], off offset:2048
	global_load_dwordx4 v[88:91], v[42:43], off offset:3072
	s_waitcnt vmcnt(31)
	v_pk_add_f32 v[10:11], v[10:11], v[92:93]
	v_pk_add_f32 v[12:13], v[12:13], v[94:95]
	s_waitcnt vmcnt(30)
	v_pk_add_f32 v[6:7], v[6:7], v[96:97]
	v_pk_add_f32 v[8:9], v[8:9], v[98:99]
	s_waitcnt vmcnt(29)
	v_pk_add_f32 v[2:3], v[2:3], v[100:101]
	v_pk_add_f32 v[4:5], v[4:5], v[102:103]
	s_waitcnt vmcnt(28)
	v_pk_add_f32 v[14:15], v[14:15], v[104:105]
	v_pk_add_f32 v[16:17], v[16:17], v[106:107]
	s_mov_b32 s16, 0x2800000
	v_add_co_u32_e32 v42, vcc, s16, v36
	s_nop 1
	v_addc_co_u32_e32 v43, vcc, 0, v37, vcc
	global_load_dwordx4 v[92:95], v[42:43], off
	global_load_dwordx4 v[96:99], v[42:43], off offset:1024
	global_load_dwordx4 v[100:103], v[42:43], off offset:2048
	global_load_dwordx4 v[104:107], v[42:43], off offset:3072
	s_waitcnt vmcnt(31)
	v_pk_add_f32 v[10:11], v[10:11], v[108:109]
	v_pk_add_f32 v[12:13], v[12:13], v[110:111]
	s_waitcnt vmcnt(30)
	v_pk_add_f32 v[6:7], v[6:7], v[112:113]
	v_pk_add_f32 v[8:9], v[8:9], v[114:115]
	s_waitcnt vmcnt(29)
	v_pk_add_f32 v[2:3], v[2:3], v[116:117]
	v_pk_add_f32 v[4:5], v[4:5], v[118:119]
	s_waitcnt vmcnt(28)
	v_pk_add_f32 v[14:15], v[14:15], v[120:121]
	v_pk_add_f32 v[16:17], v[16:17], v[122:123]
	s_waitcnt vmcnt(27)
	v_pk_add_f32 v[10:11], v[10:11], v[124:125]
	v_pk_add_f32 v[12:13], v[12:13], v[126:127]
	s_waitcnt vmcnt(26)
	v_pk_add_f32 v[6:7], v[6:7], v[128:129]
	v_pk_add_f32 v[8:9], v[8:9], v[130:131]
	s_waitcnt vmcnt(25)
	v_pk_add_f32 v[2:3], v[2:3], v[132:133]
	v_pk_add_f32 v[4:5], v[4:5], v[134:135]
	s_waitcnt vmcnt(24)
	v_pk_add_f32 v[14:15], v[14:15], v[136:137]
	v_pk_add_f32 v[16:17], v[16:17], v[138:139]
	s_waitcnt vmcnt(23)
	v_pk_add_f32 v[10:11], v[10:11], v[140:141]
	v_pk_add_f32 v[12:13], v[12:13], v[142:143]
	s_waitcnt vmcnt(22)
	v_pk_add_f32 v[6:7], v[6:7], v[144:145]
	v_pk_add_f32 v[8:9], v[8:9], v[146:147]
	s_waitcnt vmcnt(21)
	v_pk_add_f32 v[2:3], v[2:3], v[148:149]
	v_pk_add_f32 v[4:5], v[4:5], v[150:151]
	s_waitcnt vmcnt(20)
	v_pk_add_f32 v[14:15], v[14:15], v[152:153]
	v_pk_add_f32 v[16:17], v[16:17], v[154:155]
	s_waitcnt vmcnt(19)
	v_pk_add_f32 v[10:11], v[10:11], v[156:157]
	v_pk_add_f32 v[12:13], v[12:13], v[158:159]
	s_waitcnt vmcnt(18)
	v_pk_add_f32 v[6:7], v[6:7], v[160:161]
	v_pk_add_f32 v[8:9], v[8:9], v[162:163]
	s_waitcnt vmcnt(17)
	v_pk_add_f32 v[2:3], v[2:3], v[164:165]
	v_pk_add_f32 v[4:5], v[4:5], v[166:167]
	s_waitcnt vmcnt(16)
	v_pk_add_f32 v[14:15], v[14:15], v[168:169]
	v_pk_add_f32 v[16:17], v[16:17], v[170:171]
	s_waitcnt vmcnt(15)
	v_pk_add_f32 v[10:11], v[10:11], v[172:173]
	v_pk_add_f32 v[12:13], v[12:13], v[174:175]
	s_waitcnt vmcnt(14)
	v_pk_add_f32 v[6:7], v[6:7], v[176:177]
	v_pk_add_f32 v[8:9], v[8:9], v[178:179]
	s_waitcnt vmcnt(13)
	v_pk_add_f32 v[2:3], v[2:3], v[180:181]
	v_pk_add_f32 v[4:5], v[4:5], v[182:183]
	s_waitcnt vmcnt(12)
	v_pk_add_f32 v[14:15], v[14:15], v[184:185]
	v_pk_add_f32 v[16:17], v[16:17], v[186:187]
	s_waitcnt vmcnt(11)
	v_pk_add_f32 v[10:11], v[10:11], v[60:61]
	v_pk_add_f32 v[12:13], v[12:13], v[62:63]
	s_waitcnt vmcnt(10)
	v_pk_add_f32 v[6:7], v[6:7], v[64:65]
	v_pk_add_f32 v[8:9], v[8:9], v[66:67]
	s_waitcnt vmcnt(9)
	v_pk_add_f32 v[2:3], v[2:3], v[68:69]
	v_pk_add_f32 v[4:5], v[4:5], v[70:71]
	s_waitcnt vmcnt(8)
	v_pk_add_f32 v[14:15], v[14:15], v[72:73]
	v_pk_add_f32 v[16:17], v[16:17], v[74:75]
	s_waitcnt vmcnt(7)
	v_pk_add_f32 v[10:11], v[10:11], v[76:77]
	v_pk_add_f32 v[12:13], v[12:13], v[78:79]
	s_waitcnt vmcnt(6)
	v_pk_add_f32 v[6:7], v[6:7], v[80:81]
	v_pk_add_f32 v[8:9], v[8:9], v[82:83]
	s_waitcnt vmcnt(5)
	v_pk_add_f32 v[2:3], v[2:3], v[84:85]
	v_pk_add_f32 v[4:5], v[4:5], v[86:87]
	s_waitcnt vmcnt(4)
	v_pk_add_f32 v[14:15], v[14:15], v[88:89]
	v_pk_add_f32 v[16:17], v[16:17], v[90:91]
	s_waitcnt vmcnt(3)
	v_pk_add_f32 v[10:11], v[10:11], v[92:93]
	v_pk_add_f32 v[12:13], v[12:13], v[94:95]
	s_waitcnt vmcnt(2)
	v_pk_add_f32 v[6:7], v[6:7], v[96:97]
	v_pk_add_f32 v[8:9], v[8:9], v[98:99]
	s_waitcnt vmcnt(1)
	v_pk_add_f32 v[2:3], v[2:3], v[100:101]
	v_pk_add_f32 v[4:5], v[4:5], v[102:103]
	s_waitcnt vmcnt(0)
	v_pk_add_f32 v[14:15], v[14:15], v[104:105]
	v_pk_add_f32 v[16:17], v[16:17], v[106:107]
	global_store_dwordx4 v[34:35], v[10:13], off
	global_store_dwordx4 v[34:35], v[6:9], off offset:1024
	global_store_dwordx4 v[34:35], v[2:5], off offset:2048
	global_store_dwordx4 v[34:35], v[14:17], off offset:3072
	s_branch .LBB0_532

; __device__ __forceinline__ unsigned cvt_pk_bf16(float lo, float hi) { const f32x2_ v = {lo, hi}; return __builtin_bit_cast(unsigned, __builtin_convertvector(v, bf16x2_)); }
; __device__ __forceinline__ int opaque_tid() { int t = threadIdx.x; asm volatile("" : "+v"(t)); return t; }
; __device__ void norm_mod_phase(const float* srcL, const float* srcC, float* cpyL, float* cpyC, const float* g, const float* mod, bf16_t* TN, int nrows, const float* pb, int nsl) {
;     const int tid_ = opaque_tid(); const int lane = tid_ & 63, gw = opaque_bid() * 8 + (tid_ >> 6), nw = opaque_gdim() * 8;
;     for (int row = gw; row < nrows; row += nw) {
;         const bool lat = row < RL;
;         const float* sp = lat ? srcL + (size_t)row * 1024 : srcC + (size_t)(row - RL) * 1024;
;         const float* mp = mod + (lat ? (row >> 13) : 4) * 9216;
;         f32x4 v[4]; float ss = 0.f;
; #pragma unroll
;         for (int j = 0; j < 4; ++j) v[j] = *(const f32x4*)(sp + 256 * j + 4 * lane);
;         if (!lat && nsl > 0) {
;             for (int sl = 0; sl < nsl; ++sl) { const float* pp = pb + ((size_t)sl * 1024 + (row - RL)) * 1024;
; #pragma unroll
;                 for (int j = 0; j < 4; ++j) v[j] += *(const f32x4*)(pp + 256 * j + 4 * lane); }
;             float* wp = (float*)sp;
; #pragma unroll
;             for (int j = 0; j < 4; ++j) *(f32x4*)(wp + 256 * j + 4 * lane) = v[j];
;         }
; #pragma unroll
;         for (int j = 0; j < 4; ++j) ss += v[j][0] * v[j][0] + v[j][1] * v[j][1] + v[j][2] * v[j][2] + v[j][3] * v[j][3];
;         if (cpyL) { float* cp = lat ? cpyL + (size_t)row * 1024 : cpyC + (size_t)(row - RL) * 1024;
; #pragma unroll
;             for (int j = 0; j < 4; ++j) *(f32x4*)(cp + 256 * j + 4 * lane) = v[j]; }
;         ss = wave_sum(ss);
;         const float rstd = rsqrtf(ss * (1.0f / 1024.0f) + NEPS);
; #pragma unroll
;         for (int j = 0; j < 4; ++j) {
;             const int col = 256 * j + 4 * lane;
;             const f32x4 gg = *(const f32x4*)(g + col), sh = *(const f32x4*)(mp + col), sc = *(const f32x4*)(mp + 1024 + col);
;             float o[4];
; #pragma unroll
;             for (int e = 0; e < 4; ++e) o[e] = (v[j][e] * rstd * gg[e]) * (1.0f + sc[e]) + sh[e];
;             u32x2 w; w.x = cvt_pk_bf16(o[0], o[1]); w.y = cvt_pk_bf16(o[2], o[3]);
;             *(u32x2*)(TN + (size_t)row * 1024 + col) = w;
;         }
.LBB0_631:
	v_readlane_b32 s0, v254, 58
	s_mov_b32 s2, s0
	s_cmp_lg_u32 s2, 0
	v_readlane_b32 s1, v254, 59
	s_cbranch_scc0 .LBB0_644
	v_mov_b32_e32 v1, v189
	s_mov_b32 s0, s66
	s_mov_b32 s3, s94
	s_waitcnt vmcnt(0)
	v_ashrrev_i32_e32 v2, 6, v1
	v_lshl_add_u32 v18, s0, 3, v2
	s_mov_b32 s0, 0x8400
	v_cmp_gt_i32_e32 vcc, s0, v18
	s_and_saveexec_b64 s[4:5], vcc
	s_cbranch_execz .LBB0_637
	s_waitcnt lgkmcnt(0)
	v_readlane_b32 s16, v254, 56
	v_readlane_b32 s10, v254, 53
	v_readlane_b32 s17, v254, 57
	s_add_u32 s0, s16, 0x3240000
	v_readlane_b32 s11, v254, 54
	s_addc_u32 s1, s17, 0
	s_load_dwordx2 s[8:9], s[10:11], 0xb0
	s_load_dwordx2 s[14:15], s[10:11], 0x30
	s_mul_i32 s11, s2, 0x2d000
	s_mul_hi_i32 s10, s2, 0x2d000
	s_add_u32 s11, s16, s11
	s_addc_u32 s12, s17, s10
	s_add_u32 s10, s11, 0x3640000
	s_mulk_i32 s2, 0xc00
	s_addc_u32 s11, s12, 0
	s_lshl_b32 s12, s3, 3
	s_ashr_i32 s3, s2, 31
	v_lshlrev_b32_e32 v2, 2, v1
	s_lshl_b64 s[2:3], s[2:3], 2
	v_and_b32_e32 v2, 0xfc, v2
	v_ashrrev_i32_e32 v19, 31, v18
	s_waitcnt lgkmcnt(0)
	s_add_u32 s2, s14, s2
	v_lshlrev_b32_e32 v4, 2, v2
	v_mov_b32_e32 v5, v0
	v_lshlrev_b64 v[10:11], 11, v[18:19]
	v_and_b32_e32 v1, 63, v1
	s_addc_u32 s3, s15, s3
	v_lshl_add_u64 v[6:7], s[16:17], 0, v[4:5]
	s_mov_b64 s[14:15], 0x1d362000
	v_lshl_or_b32 v10, v1, 3, v10
	v_lshl_add_u64 v[20:21], v[6:7], 0, s[14:15]
	v_lshl_add_u64 v[22:23], s[2:3], 0, v[4:5]
	v_or_b32_e32 v4, 0x100, v2
	v_or_b32_e32 v6, 0x200, v2
	v_or_b32_e32 v8, 0x300, v2
	v_lshl_add_u64 v[10:11], s[16:17], 0, v[10:11]
	s_mov_b64 s[2:3], 0x36de000
	s_ashr_i32 s13, s12, 31
	v_lshl_add_u64 v[24:25], v[10:11], 0, s[2:3]
	s_lshl_b64 s[14:15], s[12:13], 11
	s_mov_b64 s[16:17], 0
	v_lshlrev_b32_e32 v26, 2, v2
	v_lshlrev_b32_e32 v28, 2, v4
	v_lshlrev_b32_e32 v30, 2, v6
	v_lshlrev_b32_e32 v32, 2, v8
	v_add_u32_e32 v118, 0xffff8000, v18
	v_cmp_lt_i32_e32 vcc, s57, v18
	v_mov_b32_e32 v120, s9
	v_mov_b32_e32 v121, s1
	v_mov_b32_e32 v119, v0
	v_cndmask_b32_e32 v118, v18, v118, vcc
	v_cndmask_b32_e32 v123, v120, v121, vcc
	v_mov_b32_e32 v120, s8
	v_mov_b32_e32 v121, s0
	v_cndmask_b32_e32 v122, v120, v121, vcc
	v_lshlrev_b64 v[118:119], 12, v[118:119]
	v_lshl_add_u64 v[118:119], v[122:123], 0, v[118:119]
	v_mov_b32_e32 v124, v26
	v_mov_b32_e32 v125, v0
	v_lshl_add_u64 v[118:119], v[118:119], 0, v[124:125]
	global_load_dwordx4 v[102:105], v[118:119], off
	global_load_dwordx4 v[106:109], v[118:119], off offset:1024
	global_load_dwordx4 v[110:113], v[118:119], off offset:2048
	global_load_dwordx4 v[114:117], v[118:119], off offset:3072
	s_waitcnt vmcnt(0)
	s_branch .LBB0_635
.LBB0_634:
	s_or_b64 exec, exec, s[2:3]
	v_min_i32_e32 v1, 0x8000, v18
	v_ashrrev_i32_e32 v1, 13, v1
	v_mul_i32_i24_e32 v34, 0x2400, v1
	v_ashrrev_i32_e32 v35, 31, v34
	v_lshl_add_u64 v[38:39], v[34:35], 2, s[10:11]
	v_mov_b32_e32 v36, v7
	v_mov_b32_e32 v37, v11
	s_mov_b64 s[2:3], 0x1000
	v_mov_b32_e32 v34, v6
	v_mov_b32_e32 v35, v10
	v_pk_mul_f32 v[36:37], v[36:37], v[36:37]
	v_lshl_add_u64 v[50:51], v[38:39], 0, s[2:3]
	v_pk_fma_f32 v[34:35], v[34:35], v[34:35], v[36:37]
	v_mov_b32_e32 v36, v8
	v_mov_b32_e32 v37, v12
	v_mov_b32_e32 v1, v220
	v_mov_b32_e32 v29, v220
	v_mov_b32_e32 v31, v220
	v_mov_b32_e32 v33, v220
	v_mov_b32_e32 v56, v220
	v_mov_b32_e32 v57, v220
	v_lshl_add_u64 v[52:53], v[38:39], 0, v[26:27]
	v_lshl_add_u64 v[42:43], v[50:51], 0, v[26:27]
	v_pk_fma_f32 v[46:47], v[36:37], v[36:37], v[34:35]
	global_load_dwordx4 v[34:37], v[22:23], off
	global_load_dwordx4 v[38:41], v[52:53], off
	global_load_dwordx4 v[60:63], v[22:23], off offset:1024
	global_load_dwordx4 v[64:67], v[22:23], off offset:2048
	global_load_dwordx4 v[68:71], v[22:23], off offset:3072
	global_load_dwordx4 v[72:75], v[52:53], off offset:1024
	global_load_dwordx4 v[76:79], v[52:53], off offset:2048
	global_load_dwordx4 v[80:83], v[52:53], off offset:3072
	global_load_dwordx4 v[84:87], v[42:43], off offset:1024
	global_load_dwordx4 v[88:91], v[42:43], off offset:2048
	global_load_dwordx4 v[92:95], v[42:43], off offset:3072
	s_nop 0
	global_load_dwordx4 v[42:45], v[42:43], off
	v_add_u32_e32 v126, s12, v18
	v_min_i32_e32 v126, s45, v126
	v_add_u32_e32 v118, 0xffff8000, v126
	v_cmp_lt_i32_e32 vcc, s57, v126
	v_mov_b32_e32 v120, s9
	v_mov_b32_e32 v121, s1
	v_mov_b32_e32 v119, v0
	v_cndmask_b32_e32 v118, v126, v118, vcc
	v_cndmask_b32_e32 v123, v120, v121, vcc
	v_mov_b32_e32 v120, s8
	v_mov_b32_e32 v121, s0
	v_cndmask_b32_e32 v122, v120, v121, vcc
	v_lshlrev_b64 v[118:119], 12, v[118:119]
	v_lshl_add_u64 v[118:119], v[122:123], 0, v[118:119]
	v_mov_b32_e32 v124, v26
	v_mov_b32_e32 v125, v0
	v_lshl_add_u64 v[118:119], v[118:119], 0, v[124:125]
	global_load_dwordx4 v[102:105], v[118:119], off
	global_load_dwordx4 v[106:109], v[118:119], off offset:1024
	global_load_dwordx4 v[110:113], v[118:119], off offset:2048
	global_load_dwordx4 v[114:117], v[118:119], off offset:3072
	v_mov_b32_e32 v48, v9
	v_mov_b32_e32 v49, v13
	v_mov_b32_e32 v54, v15
	v_mov_b32_e32 v55, v3
	v_pk_fma_f32 v[46:47], v[48:49], v[48:49], v[46:47]
	v_mov_b32_e32 v48, v14
	v_mov_b32_e32 v49, v2
	v_pk_mul_f32 v[54:55], v[54:55], v[54:55]
	v_add_f32_e32 v27, v46, v47
	v_pk_fma_f32 v[48:49], v[48:49], v[48:49], v[54:55]
	v_mov_b32_e32 v54, v16
	v_mov_b32_e32 v55, v4
	v_pk_fma_f32 v[48:49], v[54:55], v[54:55], v[48:49]
	v_mov_b32_e32 v54, v17
	v_mov_b32_e32 v55, v5
	v_pk_fma_f32 v[48:49], v[54:55], v[54:55], v[48:49]
	v_lshlrev_b32_e32 v1, 2, v1
	v_add_f32_e32 v27, v49, v27
	v_add_f32_e32 v27, v48, v27
	v_xor_b32_e32 v1, 0x80, v1
	ds_bpermute_b32 v1, v1, v27
	v_lshl_add_u64 v[18:19], v[18:19], 0, s[12:13]
	s_waitcnt lgkmcnt(0)
; __device__ __forceinline__ unsigned cvt_pk_bf16(float lo, float hi) { const f32x2_ v = {lo, hi}; return __builtin_bit_cast(unsigned, __builtin_convertvector(v, bf16x2_)); }
; __device__ void norm_mod_phase(const float* srcL, const float* srcC, float* cpyL, float* cpyC, const float* g, const float* mod, bf16_t* TN, int nrows, const float* pb, int nsl) {
;     ...
;     for (int row = gw; row < nrows; row += nw) {
;         const bool lat = row < RL;
;         const float* sp = lat ? srcL + (size_t)row * 1024 : srcC + (size_t)(row - RL) * 1024;
;         const float* mp = mod + (lat ? (row >> 13) : 4) * 9216;
;         f32x4 v[4]; float ss = 0.f;
; #pragma unroll
;         for (int j = 0; j < 4; ++j) v[j] = *(const f32x4*)(sp + 256 * j + 4 * lane);
;     ...
;         ss = wave_sum(ss);
;         const float rstd = rsqrtf(ss * (1.0f / 1024.0f) + NEPS);
; #pragma unroll
;         for (int j = 0; j < 4; ++j) {
;             const int col = 256 * j + 4 * lane;
;             const f32x4 gg = *(const f32x4*)(g + col), sh = *(const f32x4*)(mp + col), sc = *(const f32x4*)(mp + 1024 + col);
;             float o[4];
; #pragma unroll
;             for (int e = 0; e < 4; ++e) o[e] = (v[j][e] * rstd * gg[e]) * (1.0f + sc[e]) + sh[e];
;             u32x2 w; w.x = cvt_pk_bf16(o[0], o[1]); w.y = cvt_pk_bf16(o[2], o[3]);
;             *(u32x2*)(TN + (size_t)row * 1024 + col) = w;
;         }
	v_add_f32_e32 v1, v27, v1
	v_lshlrev_b32_e32 v27, 2, v29
	v_xor_b32_e32 v27, 64, v27
	ds_bpermute_b32 v27, v27, v1
	v_mov_b32_e32 v29, v0
	s_waitcnt lgkmcnt(0)
	v_add_f32_e32 v1, v1, v27
	v_lshlrev_b32_e32 v27, 2, v31
	v_xor_b32_e32 v27, 32, v27
	ds_bpermute_b32 v27, v27, v1
	v_mov_b32_e32 v31, v0
	s_waitcnt lgkmcnt(0)
	v_add_f32_e32 v1, v1, v27
	v_lshlrev_b32_e32 v27, 2, v33
	v_xor_b32_e32 v27, 16, v27
	ds_bpermute_b32 v27, v27, v1
	v_mov_b32_e32 v33, v0
	s_waitcnt lgkmcnt(0)
	v_add_f32_e32 v1, v1, v27
	v_lshlrev_b32_e32 v27, 2, v56
	v_xor_b32_e32 v27, 8, v27
	ds_bpermute_b32 v27, v27, v1
	s_waitcnt lgkmcnt(0)
	v_add_f32_e32 v1, v1, v27
	v_lshlrev_b32_e32 v27, 2, v57
	v_xor_b32_e32 v27, 4, v27
	ds_bpermute_b32 v27, v27, v1
	s_waitcnt lgkmcnt(0)
	v_add_f32_e32 v1, v1, v27
	v_fmamk_f32 v1, v1, 0x3a800000, v188
	v_mul_f32_e32 v27, 0x4b800000, v1
	v_cmp_gt_f32_e32 vcc, s44, v1
	s_nop 1
	v_cndmask_b32_e32 v1, v1, v27, vcc
	v_rsq_f32_e32 v1, v1
	s_nop 0
	v_mul_f32_e32 v27, 0x45800000, v1
	v_cndmask_b32_e32 v46, v1, v27, vcc
	v_pk_mul_f32 v[10:11], v[10:11], v[46:47] op_sel_hi:[1,0]
	v_pk_mul_f32 v[12:13], v[12:13], v[46:47] op_sel_hi:[1,0]
	s_waitcnt vmcnt(4)
	v_pk_mul_f32 v[10:11], v[34:35], v[10:11]
	v_pk_mul_f32 v[12:13], v[36:37], v[12:13]
	v_pk_add_f32 v[34:35], v[42:43], 1.0 op_sel_hi:[1,0]
	v_pk_add_f32 v[36:37], v[44:45], 1.0 op_sel_hi:[1,0]
	v_pk_fma_f32 v[10:11], v[34:35], v[10:11], v[38:39]
	v_pk_fma_f32 v[12:13], v[36:37], v[12:13], v[40:41]
	v_cvt_pk_bf16_f32 v10, v10, v11
	v_cvt_pk_bf16_f32 v11, v12, v13
	global_store_dwordx2 v[24:25], v[10:11], off
	v_pk_mul_f32 v[6:7], v[6:7], v[46:47] op_sel_hi:[1,0]
	v_pk_mul_f32 v[8:9], v[8:9], v[46:47] op_sel_hi:[1,0]
	v_pk_mul_f32 v[2:3], v[2:3], v[46:47] op_sel_hi:[1,0]
	v_pk_mul_f32 v[4:5], v[4:5], v[46:47] op_sel_hi:[1,0]
	v_pk_mul_f32 v[14:15], v[14:15], v[46:47] op_sel_hi:[1,0]
	v_pk_mul_f32 v[16:17], v[16:17], v[46:47] op_sel_hi:[1,0]
	v_cmp_lt_i32_e32 vcc, s45, v18
	s_or_b64 s[16:17], vcc, s[16:17]
	v_pk_mul_f32 v[6:7], v[60:61], v[6:7]
	v_pk_add_f32 v[10:11], v[84:85], 1.0 op_sel_hi:[1,0]
	v_pk_mul_f32 v[8:9], v[62:63], v[8:9]
	v_pk_add_f32 v[12:13], v[86:87], 1.0 op_sel_hi:[1,0]
	v_pk_fma_f32 v[6:7], v[10:11], v[6:7], v[72:73]
	v_pk_fma_f32 v[8:9], v[12:13], v[8:9], v[74:75]
	v_cvt_pk_bf16_f32 v6, v6, v7
	v_cvt_pk_bf16_f32 v7, v8, v9
	global_store_dwordx2 v[24:25], v[6:7], off offset:512
	v_pk_mul_f32 v[2:3], v[64:65], v[2:3]
	v_pk_add_f32 v[6:7], v[88:89], 1.0 op_sel_hi:[1,0]
	v_pk_mul_f32 v[4:5], v[66:67], v[4:5]
	v_pk_add_f32 v[8:9], v[90:91], 1.0 op_sel_hi:[1,0]
	v_pk_fma_f32 v[2:3], v[2:3], v[6:7], v[76:77]
	v_pk_fma_f32 v[4:5], v[4:5], v[8:9], v[78:79]
	v_cvt_pk_bf16_f32 v2, v2, v3
	v_cvt_pk_bf16_f32 v3, v4, v5
	global_store_dwordx2 v[24:25], v[2:3], off offset:1024
	v_pk_mul_f32 v[2:3], v[14:15], v[68:69]
	v_pk_add_f32 v[6:7], v[92:93], 1.0 op_sel_hi:[1,0]
	v_pk_mul_f32 v[4:5], v[16:17], v[70:71]
	v_pk_add_f32 v[8:9], v[94:95], 1.0 op_sel_hi:[1,0]
	v_pk_fma_f32 v[2:3], v[2:3], v[6:7], v[80:81]
	v_pk_fma_f32 v[4:5], v[4:5], v[8:9], v[82:83]
	v_cvt_pk_bf16_f32 v2, v2, v3
	v_cvt_pk_bf16_f32 v3, v4, v5
	global_store_dwordx2 v[24:25], v[2:3], off offset:1536
	v_lshl_add_u64 v[24:25], v[24:25], 0, s[14:15]
	s_andn2_b64 exec, exec, s[16:17]
	s_cbranch_execz .LBB0_637
.LBB0_635:
	v_add_u32_e32 v36, 0xffff8000, v18
	v_cmp_lt_i32_e32 vcc, s57, v18
	v_mov_b32_e32 v1, s9
	v_mov_b32_e32 v4, s1
	v_cndmask_b32_e64 v3, v19, 0, vcc
	v_cndmask_b32_e32 v2, v18, v36, vcc
	v_cndmask_b32_e32 v5, v1, v4, vcc
	v_mov_b32_e32 v1, s8
	v_mov_b32_e32 v4, s0
	v_cndmask_b32_e32 v4, v1, v4, vcc
	v_lshlrev_b64 v[2:3], 12, v[2:3]
	v_lshl_add_u64 v[2:3], v[4:5], 0, v[2:3]
	v_mov_b32_e32 v27, v0
	v_lshl_add_u64 v[34:35], v[2:3], 0, v[26:27]
	s_waitcnt vmcnt(4)
	v_mov_b64_e32 v[10:11], v[102:103]
	v_mov_b64_e32 v[12:13], v[104:105]
	v_mov_b64_e32 v[6:7], v[106:107]
	v_mov_b64_e32 v[8:9], v[108:109]
	v_mov_b64_e32 v[2:3], v[110:111]
	v_mov_b64_e32 v[4:5], v[112:113]
	v_mov_b64_e32 v[14:15], v[114:115]
	v_mov_b64_e32 v[16:17], v[116:117]
	v_mov_b32_e32 v37, v0
	s_and_saveexec_b64 s[2:3], vcc
	s_cbranch_execz .LBB0_634
	v_lshlrev_b64 v[36:37], 12, v[36:37]
	v_lshl_add_u64 v[36:37], v[20:21], 0, v[36:37]
	global_load_dwordx4 v[60:63], v[36:37], off
	global_load_dwordx4 v[64:67], v[36:37], off offset:1024
	global_load_dwordx4 v[68:71], v[36:37], off offset:2048
	global_load_dwordx4 v[72:75], v[36:37], off offset:3072
	s_mov_b32 s18, 0x400000
	v_add_co_u32_e32 v42, vcc, s18, v36
	s_nop 1
	v_addc_co_u32_e32 v43, vcc, 0, v37, vcc
	global_load_dwordx4 v[76:79], v[42:43], off
	global_load_dwordx4 v[80:83], v[42:43], off offset:1024
	global_load_dwordx4 v[84:87], v[42:43], off offset:2048
	global_load_dwordx4 v[88:91], v[42:43], off offset:3072
	s_mov_b32 s18, 0x800000
	v_add_co_u32_e32 v42, vcc, s18, v36
	s_nop 1
	v_addc_co_u32_e32 v43, vcc, 0, v37, vcc
	global_load_dwordx4 v[92:95], v[42:43], off
	global_load_dwordx4 v[96:99], v[42:43], off offset:1024
	global_load_dwordx4 v[100:103], v[42:43], off offset:2048
	global_load_dwordx4 v[104:107], v[42:43], off offset:3072
	s_mov_b32 s18, 0xc00000
	v_add_co_u32_e32 v42, vcc, s18, v36
	s_nop 1
	v_addc_co_u32_e32 v43, vcc, 0, v37, vcc
	global_load_dwordx4 v[108:111], v[42:43], off
	global_load_dwordx4 v[112:115], v[42:43], off offset:1024
	global_load_dwordx4 v[116:119], v[42:43], off offset:2048
	global_load_dwordx4 v[120:123], v[42:43], off offset:3072
	s_mov_b32 s18, 0x1000000
	v_add_co_u32_e32 v42, vcc, s18, v36
	s_nop 1
	v_addc_co_u32_e32 v43, vcc, 0, v37, vcc
	global_load_dwordx4 v[124:127], v[42:43], off
	global_load_dwordx4 v[128:131], v[42:43], off offset:1024
	global_load_dwordx4 v[132:135], v[42:43], off offset:2048
	global_load_dwordx4 v[136:139], v[42:43], off offset:3072
	s_mov_b32 s18, 0x1400000
	v_add_co_u32_e32 v42, vcc, s18, v36
	s_nop 1
	v_addc_co_u32_e32 v43, vcc, 0, v37, vcc
	global_load_dwordx4 v[140:143], v[42:43], off
	global_load_dwordx4 v[144:147], v[42:43], off offset:1024
	global_load_dwordx4 v[148:151], v[42:43], off offset:2048
	global_load_dwordx4 v[152:155], v[42:43], off offset:3072
	s_mov_b32 s18, 0x1800000
	v_add_co_u32_e32 v42, vcc, s18, v36
	s_nop 1
	v_addc_co_u32_e32 v43, vcc, 0, v37, vcc
	global_load_dwordx4 v[156:159], v[42:43], off
	global_load_dwordx4 v[160:163], v[42:43], off offset:1024
	global_load_dwordx4 v[164:167], v[42:43], off offset:2048
	global_load_dwordx4 v[168:171], v[42:43], off offset:3072
	s_mov_b32 s18, 0x1c00000
	v_add_co_u32_e32 v42, vcc, s18, v36
	s_nop 1
	v_addc_co_u32_e32 v43, vcc, 0, v37, vcc
	global_load_dwordx4 v[172:175], v[42:43], off
	global_load_dwordx4 v[176:179], v[42:43], off offset:1024
	global_load_dwordx4 v[180:183], v[42:43], off offset:2048
	global_load_dwordx4 v[184:187], v[42:43], off offset:3072
	s_waitcnt vmcnt(31)
; __device__ void norm_mod_phase(const float* srcL, const float* srcC, float* cpyL, float* cpyC, const float* g, const float* mod, bf16_t* TN, int nrows, const float* pb, int nsl) {
;     ...
;         if (!lat && nsl > 0) {
;             for (int sl = 0; sl < nsl; ++sl) { const float* pp = pb + ((size_t)sl * 1024 + (row - RL)) * 1024;
; #pragma unroll
;                 for (int j = 0; j < 4; ++j) v[j] += *(const f32x4*)(pp + 256 * j + 4 * lane); }
;             float* wp = (float*)sp;
; #pragma unroll
;             for (int j = 0; j < 4; ++j) *(f32x4*)(wp + 256 * j + 4 * lane) = v[j];
;         }
	v_pk_add_f32 v[10:11], v[10:11], v[60:61]
	v_pk_add_f32 v[12:13], v[12:13], v[62:63]
	s_waitcnt vmcnt(30)
	v_pk_add_f32 v[6:7], v[6:7], v[64:65]
	v_pk_add_f32 v[8:9], v[8:9], v[66:67]
	s_waitcnt vmcnt(29)
	v_pk_add_f32 v[2:3], v[2:3], v[68:69]
	v_pk_add_f32 v[4:5], v[4:5], v[70:71]
	s_waitcnt vmcnt(28)
	v_pk_add_f32 v[14:15], v[14:15], v[72:73]
	v_pk_add_f32 v[16:17], v[16:17], v[74:75]
	s_mov_b32 s18, 0x2000000
	v_add_co_u32_e32 v42, vcc, s18, v36
	s_nop 1
	v_addc_co_u32_e32 v43, vcc, 0, v37, vcc
	global_load_dwordx4 v[60:63], v[42:43], off
	global_load_dwordx4 v[64:67], v[42:43], off offset:1024
	global_load_dwordx4 v[68:71], v[42:43], off offset:2048
	global_load_dwordx4 v[72:75], v[42:43], off offset:3072
	s_waitcnt vmcnt(31)
	v_pk_add_f32 v[10:11], v[10:11], v[76:77]
	v_pk_add_f32 v[12:13], v[12:13], v[78:79]
	s_waitcnt vmcnt(30)
	v_pk_add_f32 v[6:7], v[6:7], v[80:81]
	v_pk_add_f32 v[8:9], v[8:9], v[82:83]
	s_waitcnt vmcnt(29)
	v_pk_add_f32 v[2:3], v[2:3], v[84:85]
	v_pk_add_f32 v[4:5], v[4:5], v[86:87]
	s_waitcnt vmcnt(28)
	v_pk_add_f32 v[14:15], v[14:15], v[88:89]
	v_pk_add_f32 v[16:17], v[16:17], v[90:91]
	s_mov_b32 s18, 0x2400000
	v_add_co_u32_e32 v42, vcc, s18, v36
	s_nop 1
	v_addc_co_u32_e32 v43, vcc, 0, v37, vcc
	global_load_dwordx4 v[76:79], v[42:43], off
	global_load_dwordx4 v[80:83], v[42:43], off offset:1024
	global_load_dwordx4 v[84:87], v[42:43], off offset:2048
	global_load_dwordx4 v[88:91], v[42:43], off offset:3072
	s_waitcnt vmcnt(31)
	v_pk_add_f32 v[10:11], v[10:11], v[92:93]
	v_pk_add_f32 v[12:13], v[12:13], v[94:95]
	s_waitcnt vmcnt(30)
	v_pk_add_f32 v[6:7], v[6:7], v[96:97]
	v_pk_add_f32 v[8:9], v[8:9], v[98:99]
	s_waitcnt vmcnt(29)
	v_pk_add_f32 v[2:3], v[2:3], v[100:101]
	v_pk_add_f32 v[4:5], v[4:5], v[102:103]
	s_waitcnt vmcnt(28)
	v_pk_add_f32 v[14:15], v[14:15], v[104:105]
	v_pk_add_f32 v[16:17], v[16:17], v[106:107]
	s_mov_b32 s18, 0x2800000
	v_add_co_u32_e32 v42, vcc, s18, v36
	s_nop 1
	v_addc_co_u32_e32 v43, vcc, 0, v37, vcc
	global_load_dwordx4 v[92:95], v[42:43], off
	global_load_dwordx4 v[96:99], v[42:43], off offset:1024
	global_load_dwordx4 v[100:103], v[42:43], off offset:2048
	global_load_dwordx4 v[104:107], v[42:43], off offset:3072
	s_waitcnt vmcnt(31)
	v_pk_add_f32 v[10:11], v[10:11], v[108:109]
	v_pk_add_f32 v[12:13], v[12:13], v[110:111]
	s_waitcnt vmcnt(30)
	v_pk_add_f32 v[6:7], v[6:7], v[112:113]
	v_pk_add_f32 v[8:9], v[8:9], v[114:115]
	s_waitcnt vmcnt(29)
	v_pk_add_f32 v[2:3], v[2:3], v[116:117]
	v_pk_add_f32 v[4:5], v[4:5], v[118:119]
	s_waitcnt vmcnt(28)
	v_pk_add_f32 v[14:15], v[14:15], v[120:121]
	v_pk_add_f32 v[16:17], v[16:17], v[122:123]
	s_waitcnt vmcnt(27)
	v_pk_add_f32 v[10:11], v[10:11], v[124:125]
	v_pk_add_f32 v[12:13], v[12:13], v[126:127]
	s_waitcnt vmcnt(26)
	v_pk_add_f32 v[6:7], v[6:7], v[128:129]
	v_pk_add_f32 v[8:9], v[8:9], v[130:131]
	s_waitcnt vmcnt(25)
	v_pk_add_f32 v[2:3], v[2:3], v[132:133]
	v_pk_add_f32 v[4:5], v[4:5], v[134:135]
	s_waitcnt vmcnt(24)
	v_pk_add_f32 v[14:15], v[14:15], v[136:137]
	v_pk_add_f32 v[16:17], v[16:17], v[138:139]
	s_waitcnt vmcnt(23)
	v_pk_add_f32 v[10:11], v[10:11], v[140:141]
	v_pk_add_f32 v[12:13], v[12:13], v[142:143]
	s_waitcnt vmcnt(22)
	v_pk_add_f32 v[6:7], v[6:7], v[144:145]
	v_pk_add_f32 v[8:9], v[8:9], v[146:147]
	s_waitcnt vmcnt(21)
	v_pk_add_f32 v[2:3], v[2:3], v[148:149]
	v_pk_add_f32 v[4:5], v[4:5], v[150:151]
	s_waitcnt vmcnt(20)
	v_pk_add_f32 v[14:15], v[14:15], v[152:153]
	v_pk_add_f32 v[16:17], v[16:17], v[154:155]
	s_waitcnt vmcnt(19)
	v_pk_add_f32 v[10:11], v[10:11], v[156:157]
	v_pk_add_f32 v[12:13], v[12:13], v[158:159]
	s_waitcnt vmcnt(18)
	v_pk_add_f32 v[6:7], v[6:7], v[160:161]
	v_pk_add_f32 v[8:9], v[8:9], v[162:163]
	s_waitcnt vmcnt(17)
	v_pk_add_f32 v[2:3], v[2:3], v[164:165]
	v_pk_add_f32 v[4:5], v[4:5], v[166:167]
	s_waitcnt vmcnt(16)
	v_pk_add_f32 v[14:15], v[14:15], v[168:169]
	v_pk_add_f32 v[16:17], v[16:17], v[170:171]
	s_waitcnt vmcnt(15)
	v_pk_add_f32 v[10:11], v[10:11], v[172:173]
	v_pk_add_f32 v[12:13], v[12:13], v[174:175]
	s_waitcnt vmcnt(14)
	v_pk_add_f32 v[6:7], v[6:7], v[176:177]
	v_pk_add_f32 v[8:9], v[8:9], v[178:179]
	s_waitcnt vmcnt(13)
	v_pk_add_f32 v[2:3], v[2:3], v[180:181]
	v_pk_add_f32 v[4:5], v[4:5], v[182:183]
	s_waitcnt vmcnt(12)
	v_pk_add_f32 v[14:15], v[14:15], v[184:185]
	v_pk_add_f32 v[16:17], v[16:17], v[186:187]
	s_waitcnt vmcnt(11)
	v_pk_add_f32 v[10:11], v[10:11], v[60:61]
	v_pk_add_f32 v[12:13], v[12:13], v[62:63]
	s_waitcnt vmcnt(10)
	v_pk_add_f32 v[6:7], v[6:7], v[64:65]
	v_pk_add_f32 v[8:9], v[8:9], v[66:67]
	s_waitcnt vmcnt(9)
	v_pk_add_f32 v[2:3], v[2:3], v[68:69]
	v_pk_add_f32 v[4:5], v[4:5], v[70:71]
	s_waitcnt vmcnt(8)
	v_pk_add_f32 v[14:15], v[14:15], v[72:73]
	v_pk_add_f32 v[16:17], v[16:17], v[74:75]
	s_waitcnt vmcnt(7)
	v_pk_add_f32 v[10:11], v[10:11], v[76:77]
	v_pk_add_f32 v[12:13], v[12:13], v[78:79]
	s_waitcnt vmcnt(6)
	v_pk_add_f32 v[6:7], v[6:7], v[80:81]
	v_pk_add_f32 v[8:9], v[8:9], v[82:83]
	s_waitcnt vmcnt(5)
	v_pk_add_f32 v[2:3], v[2:3], v[84:85]
	v_pk_add_f32 v[4:5], v[4:5], v[86:87]
	s_waitcnt vmcnt(4)
	v_pk_add_f32 v[14:15], v[14:15], v[88:89]
	v_pk_add_f32 v[16:17], v[16:17], v[90:91]
	s_waitcnt vmcnt(3)
	v_pk_add_f32 v[10:11], v[10:11], v[92:93]
	v_pk_add_f32 v[12:13], v[12:13], v[94:95]
	s_waitcnt vmcnt(2)
	v_pk_add_f32 v[6:7], v[6:7], v[96:97]
	v_pk_add_f32 v[8:9], v[8:9], v[98:99]
	s_waitcnt vmcnt(1)
	v_pk_add_f32 v[2:3], v[2:3], v[100:101]
	v_pk_add_f32 v[4:5], v[4:5], v[102:103]
	s_waitcnt vmcnt(0)
	v_pk_add_f32 v[14:15], v[14:15], v[104:105]
	v_pk_add_f32 v[16:17], v[16:17], v[106:107]
	global_store_dwordx4 v[34:35], v[10:13], off
	global_store_dwordx4 v[34:35], v[6:9], off offset:1024
	global_store_dwordx4 v[34:35], v[2:5], off offset:2048
	global_store_dwordx4 v[34:35], v[14:17], off offset:3072
	s_branch .LBB0_634
